# v056 idle CUs of glu / top-k phases convert 2 items per wave (one trip), barrier sequence 57344 items
# speedup vs baseline: 1.0033x; 1.0033x over previous
; DEV void phase_prologue_a(const Frame& F0) {
;     ...
;         constexpr int D_ITEMS = (FF / 64) * 32;
;         for (int it = F.gw; it < NE * D_ITEMS; it += F.NGW) { const int e = it / D_ITEMS, r = it % D_ITEMS, kb = r / 32, nb = r % 32;
;             tr_item(GIN(I_WDOWN) + ((size_t)l * NE + e) * FF * 1024, 1024, 32 * nb, 64 * kb, (bf16_t*)(F.ws + WS_WD) + ((size_t)l * NE + e) * 1024 * FF, FF, 32 * nb, scr, F.lane); }
.Lpro_dn_do:
	s_lshl_b64 s[20:21], s[2:3], 4
	s_mov_b32 s2, s31
	v_readlane_b32 s100, v255, 51
	s_cmp_lg_u32 s100, 0x100
	s_cbranch_scc1 .Lpro_dn_all
	s_cmp_lg_u32 s14, 0
	s_cbranch_scc1 .Lpro_dn_all
	s_add_i32 s2, s2, 0x2f00

; #define WAIT_VM(n) do {} while (0)
; #define WAIT_ALL() do {} while (0)
; #define LAUNDER_S(x) do {} while (0)
; #define WAIT_VM(n) asm volatile("s_waitcnt vmcnt(" #n ")" ::: "memory")
; #define WAIT_ALL() asm volatile("s_waitcnt vmcnt(0) lgkmcnt(0)" ::: "memory")
; #define LAUNDER_S(x) asm volatile("" : "+s"(x))
; DEV int lane_id() { return (int)__builtin_amdgcn_mbcnt_hi(~0u, __builtin_amdgcn_mbcnt_lo(~0u, 0u)); }
; DEV unsigned xb_add(unsigned* p, unsigned v) { return __hip_atomic_fetch_add(p, v, __ATOMIC_RELAXED, __HIP_MEMORY_SCOPE_AGENT); }
; DEV void xcd_barrier(const XcdBarrier& b) {
;     WAIT_VM(0);
;     __syncthreads();
;     int bw = b.wave; LAUNDER_S(bw);
;     if (bw == 0 && lane_id() == 0) {
;         unsigned* bar = b.bar; LAUNDER_S(bar);
;         unsigned bx = b.x; LAUNDER_S(bx);
;         WAIT_ALL();
;         unsigned nloc = b.st[0], nx = b.st[1];
;         if (nloc == 0u) { xcd_barrier_complete(bar, bx, nloc, nx); b.st[0] = nloc; b.st[1] = nx; }
;         const unsigned old = xb_add(&bar[XB_XSUB(bx)], 1u);
;         const unsigned gen = old / nloc;
;         if (old + 1u == (gen + 1u) * nloc) {
; DEV void phase_prologue_a(const Frame& F0) {
;     ...
;         constexpr int GU_NB = 2 * FF / 32, GU_ITEMS = 16 * GU_NB;
;         for (int it = F.gw; it < NE * GU_ITEMS; it += F.NGW) { const int e = it / GU_ITEMS, r = it % GU_ITEMS, kb = r / GU_NB, nb = r % GU_NB; const int d0 = 32 * nb, j = d0 >> 8, w = d0 & 255;
;             const float* src = (w < 128 ? GIN(I_WGATE) : GIN(I_WUP)) + ((size_t)l * NE + e) * 1024 * FF;
;             tr_item(src, FF, 128 * j + (w & 127), 64 * kb, (bf16_t*)(F.ws + WS_WGU) + ((size_t)l * NE + e) * 2 * FF * 1024, 1024, d0, scr, F.lane); }
.LBB0_115:
	s_or_b64 exec, exec, s[30:31]
	s_cselect_b32 s38, 1, 0
	v_writelane_b32 v255, s38, 61
	v_readlane_b32 s38, v255, 59
	s_add_i32 s39, s38, 1
	v_writelane_b32 v255, s39, 59
	s_mov_b32 s41, 0
	v_readlane_b32 s39, v251, 29
	s_cmp_eq_u32 s39, 0
	s_cbranch_scc1 .Lbw0_none
	v_readlane_b32 s40, v255, 51
	s_cmp_lg_u32 s40, 0x100
	s_cbranch_scc1 .Lbw0_none
	v_readlane_b32 s40, v255, 48
	s_mul_i32 s40, s40, 7
	s_mul_i32 s38, s38, 0x700
	s_add_i32 s40, s40, s38
	s_add_i32 s40, s40, s39
	s_add_i32 s40, s40, -1
	s_cmp_lt_u32 s40, 0xe000
	s_cbranch_scc0 .Lbw0_none
	s_mov_b32 s41, 0
	s_add_i32 s40, s40, 0x3c00
	s_cmp_lt_u32 s40, 0x7800
	s_cbranch_scc1 .Lbw0_have
	s_mov_b32 s41, 1
	s_sub_i32 s40, s40, 0x7800
	s_cmp_lt_u32 s40, 0x4400
	s_cbranch_scc1 .Lbw0_have
	s_mov_b32 s41, 2
	s_sub_i32 s40, s40, 0x4400
	s_cmp_lt_u32 s40, 0x2a80
	s_cbranch_scc1 .Lbw0_have
	s_mov_b32 s41, 3
	s_sub_i32 s40, s40, 0x2a80

; #define WAIT_VM(n) do {} while (0)
; #define WAIT_ALL() do {} while (0)
; #define LAUNDER_S(x) do {} while (0)
; #define WAIT_VM(n) asm volatile("s_waitcnt vmcnt(" #n ")" ::: "memory")
; #define WAIT_ALL() asm volatile("s_waitcnt vmcnt(0) lgkmcnt(0)" ::: "memory")
; #define LAUNDER_S(x) asm volatile("" : "+s"(x))
; DEV int lane_id() { return (int)__builtin_amdgcn_mbcnt_hi(~0u, __builtin_amdgcn_mbcnt_lo(~0u, 0u)); }
; DEV unsigned xb_add(unsigned* p, unsigned v) { return __hip_atomic_fetch_add(p, v, __ATOMIC_RELAXED, __HIP_MEMORY_SCOPE_AGENT); }
; DEV void xcd_barrier(const XcdBarrier& b) {
;     WAIT_VM(0);
;     __syncthreads();
;     int bw = b.wave; LAUNDER_S(bw);
;     if (bw == 0 && lane_id() == 0) {
;         unsigned* bar = b.bar; LAUNDER_S(bar);
;         unsigned bx = b.x; LAUNDER_S(bx);
;         WAIT_ALL();
;         unsigned nloc = b.st[0], nx = b.st[1];
;         if (nloc == 0u) { xcd_barrier_complete(bar, bx, nloc, nx); b.st[0] = nloc; b.st[1] = nx; }
;         const unsigned old = xb_add(&bar[XB_XSUB(bx)], 1u);
;         const unsigned gen = old / nloc;
;         if (old + 1u == (gen + 1u) * nloc) {
; DEV void phase_prologue_a(const Frame& F0) {
;     ...
;         constexpr int GU_NB = 2 * FF / 32, GU_ITEMS = 16 * GU_NB;
;         for (int it = F.gw; it < NE * GU_ITEMS; it += F.NGW) { const int e = it / GU_ITEMS, r = it % GU_ITEMS, kb = r / GU_NB, nb = r % GU_NB; const int d0 = 32 * nb, j = d0 >> 8, w = d0 & 255;
;             const float* src = (w < 128 ? GIN(I_WGATE) : GIN(I_WUP)) + ((size_t)l * NE + e) * 1024 * FF;
;             tr_item(src, FF, 128 * j + (w & 127), 64 * kb, (bf16_t*)(F.ws + WS_WGU) + ((size_t)l * NE + e) * 2 * FF * 1024, 1024, d0, scr, F.lane); }
.LBB0_241:
	v_writelane_b32 v253, s58, 51
	s_nop 1
	v_writelane_b32 v253, s59, 52
	v_writelane_b32 v253, s56, 53
	s_nop 1
	v_writelane_b32 v253, s57, 54
	s_or_b64 exec, exec, s[34:35]
	s_cselect_b32 s38, 1, 0
	v_writelane_b32 v255, s38, 61
	v_readlane_b32 s38, v255, 59
	s_add_i32 s39, s38, 1
	v_writelane_b32 v255, s39, 59
	s_mov_b32 s41, 0
	v_readlane_b32 s39, v251, 29
	s_cmp_eq_u32 s39, 0
	s_cbranch_scc1 .Lbw2_none
	v_readlane_b32 s40, v255, 51
	s_cmp_lg_u32 s40, 0x100
	s_cbranch_scc1 .Lbw2_none
	v_readlane_b32 s40, v255, 48
	s_mul_i32 s40, s40, 7
	s_mul_i32 s38, s38, 0x700
	s_add_i32 s40, s40, s38
	s_add_i32 s40, s40, s39
	s_add_i32 s40, s40, -1
	s_cmp_lt_u32 s40, 0xe000
	s_cbranch_scc0 .Lbw2_none
	s_mov_b32 s41, 0
	s_add_i32 s40, s40, 0x3c00
	s_cmp_lt_u32 s40, 0x7800
	s_cbranch_scc1 .Lbw2_have
	s_mov_b32 s41, 1
	s_sub_i32 s40, s40, 0x7800
	s_cmp_lt_u32 s40, 0x4400
	s_cbranch_scc1 .Lbw2_have
	s_mov_b32 s41, 2
	s_sub_i32 s40, s40, 0x4400
	s_cmp_lt_u32 s40, 0x2a80
	s_cbranch_scc1 .Lbw2_have
	s_mov_b32 s41, 3
	s_sub_i32 s40, s40, 0x2a80

; #define WAIT_VM(n) do {} while (0)
; #define WAIT_ALL() do {} while (0)
; #define LAUNDER_S(x) do {} while (0)
; #define WAIT_VM(n) asm volatile("s_waitcnt vmcnt(" #n ")" ::: "memory")
; #define WAIT_ALL() asm volatile("s_waitcnt vmcnt(0) lgkmcnt(0)" ::: "memory")
; #define LAUNDER_S(x) asm volatile("" : "+s"(x))
; DEV int lane_id() { return (int)__builtin_amdgcn_mbcnt_hi(~0u, __builtin_amdgcn_mbcnt_lo(~0u, 0u)); }
; DEV unsigned xb_add(unsigned* p, unsigned v) { return __hip_atomic_fetch_add(p, v, __ATOMIC_RELAXED, __HIP_MEMORY_SCOPE_AGENT); }
; DEV void xcd_barrier(const XcdBarrier& b) {
;     WAIT_VM(0);
;     __syncthreads();
;     int bw = b.wave; LAUNDER_S(bw);
;     if (bw == 0 && lane_id() == 0) {
;         unsigned* bar = b.bar; LAUNDER_S(bar);
;         unsigned bx = b.x; LAUNDER_S(bx);
;         WAIT_ALL();
;         unsigned nloc = b.st[0], nx = b.st[1];
;         if (nloc == 0u) { xcd_barrier_complete(bar, bx, nloc, nx); b.st[0] = nloc; b.st[1] = nx; }
;         const unsigned old = xb_add(&bar[XB_XSUB(bx)], 1u);
;         const unsigned gen = old / nloc;
;         if (old + 1u == (gen + 1u) * nloc) {
; DEV void phase_prologue_a(const Frame& F0) {
;     ...
;         constexpr int GU_NB = 2 * FF / 32, GU_ITEMS = 16 * GU_NB;
;         for (int it = F.gw; it < NE * GU_ITEMS; it += F.NGW) { const int e = it / GU_ITEMS, r = it % GU_ITEMS, kb = r / GU_NB, nb = r % GU_NB; const int d0 = 32 * nb, j = d0 >> 8, w = d0 & 255;
;             const float* src = (w < 128 ? GIN(I_WGATE) : GIN(I_WUP)) + ((size_t)l * NE + e) * 1024 * FF;
;             tr_item(src, FF, 128 * j + (w & 127), 64 * kb, (bf16_t*)(F.ws + WS_WGU) + ((size_t)l * NE + e) * 2 * FF * 1024, 1024, d0, scr, F.lane); }
.LBB0_422:
	s_or_b64 exec, exec, s[34:35]
	s_cselect_b32 s38, 1, 0
	v_writelane_b32 v255, s38, 61
	v_readlane_b32 s38, v255, 59
	s_add_i32 s39, s38, 1
	v_writelane_b32 v255, s39, 59
	s_mov_b32 s41, 0
	v_readlane_b32 s39, v251, 29
	s_cmp_eq_u32 s39, 0
	s_cbranch_scc1 .Lbw3_none
	v_readlane_b32 s40, v255, 51
	s_cmp_lg_u32 s40, 0x100
	s_cbranch_scc1 .Lbw3_none
	v_readlane_b32 s40, v255, 48
	s_mul_i32 s40, s40, 7
	s_mul_i32 s38, s38, 0x700
	s_add_i32 s40, s40, s38
	s_add_i32 s40, s40, s39
	s_add_i32 s40, s40, -1
	s_cmp_lt_u32 s40, 0xe000
	s_cbranch_scc0 .Lbw3_none
	s_mov_b32 s41, 0
	s_add_i32 s40, s40, 0x3c00
	s_cmp_lt_u32 s40, 0x7800
	s_cbranch_scc1 .Lbw3_have
	s_mov_b32 s41, 1
	s_sub_i32 s40, s40, 0x7800
	s_cmp_lt_u32 s40, 0x4400
	s_cbranch_scc1 .Lbw3_have
	s_mov_b32 s41, 2
	s_sub_i32 s40, s40, 0x4400
	s_cmp_lt_u32 s40, 0x2a80
	s_cbranch_scc1 .Lbw3_have
	s_mov_b32 s41, 3
	s_sub_i32 s40, s40, 0x2a80

; #define WAIT_VM(n) do {} while (0)
; #define WAIT_ALL() do {} while (0)
; #define LAUNDER_S(x) do {} while (0)
; #define WAIT_VM(n) asm volatile("s_waitcnt vmcnt(" #n ")" ::: "memory")
; #define WAIT_ALL() asm volatile("s_waitcnt vmcnt(0) lgkmcnt(0)" ::: "memory")
; #define LAUNDER_S(x) asm volatile("" : "+s"(x))
; DEV int lane_id() { return (int)__builtin_amdgcn_mbcnt_hi(~0u, __builtin_amdgcn_mbcnt_lo(~0u, 0u)); }
; DEV unsigned xb_add(unsigned* p, unsigned v) { return __hip_atomic_fetch_add(p, v, __ATOMIC_RELAXED, __HIP_MEMORY_SCOPE_AGENT); }
; DEV void xcd_barrier(const XcdBarrier& b) {
;     WAIT_VM(0);
;     __syncthreads();
;     int bw = b.wave; LAUNDER_S(bw);
;     if (bw == 0 && lane_id() == 0) {
;         unsigned* bar = b.bar; LAUNDER_S(bar);
;         unsigned bx = b.x; LAUNDER_S(bx);
;         WAIT_ALL();
;         unsigned nloc = b.st[0], nx = b.st[1];
;         if (nloc == 0u) { xcd_barrier_complete(bar, bx, nloc, nx); b.st[0] = nloc; b.st[1] = nx; }
;         const unsigned old = xb_add(&bar[XB_XSUB(bx)], 1u);
;         const unsigned gen = old / nloc;
;         if (old + 1u == (gen + 1u) * nloc) {
; DEV void phase_prologue_a(const Frame& F0) {
;     ...
;         constexpr int GU_NB = 2 * FF / 32, GU_ITEMS = 16 * GU_NB;
;         for (int it = F.gw; it < NE * GU_ITEMS; it += F.NGW) { const int e = it / GU_ITEMS, r = it % GU_ITEMS, kb = r / GU_NB, nb = r % GU_NB; const int d0 = 32 * nb, j = d0 >> 8, w = d0 & 255;
;             const float* src = (w < 128 ? GIN(I_WGATE) : GIN(I_WUP)) + ((size_t)l * NE + e) * 1024 * FF;
;             tr_item(src, FF, 128 * j + (w & 127), 64 * kb, (bf16_t*)(F.ws + WS_WGU) + ((size_t)l * NE + e) * 2 * FF * 1024, 1024, d0, scr, F.lane); }
.Lxb4_join:
.LBB0_811:
	s_or_b64 exec, exec, s[34:35]
	s_cselect_b32 s38, 1, 0
	v_writelane_b32 v255, s38, 61
	v_readlane_b32 s38, v255, 59
	s_add_i32 s39, s38, 1
	v_writelane_b32 v255, s39, 59
	s_mov_b32 s41, 0
	v_readlane_b32 s39, v251, 29
	s_cmp_eq_u32 s39, 0
	s_cbranch_scc1 .Lbw4_none
	v_readlane_b32 s40, v255, 51
	s_cmp_lg_u32 s40, 0x100
	s_cbranch_scc1 .Lbw4_none
	v_readlane_b32 s40, v255, 48
	s_mul_i32 s40, s40, 7
	s_mul_i32 s38, s38, 0x700
	s_add_i32 s40, s40, s38
	s_add_i32 s40, s40, s39
	s_add_i32 s40, s40, -1
	s_cmp_lt_u32 s40, 0xe000
	s_cbranch_scc0 .Lbw4_none
	s_mov_b32 s41, 0
	s_add_i32 s40, s40, 0x3c00
	s_cmp_lt_u32 s40, 0x7800
	s_cbranch_scc1 .Lbw4_have
	s_mov_b32 s41, 1
	s_sub_i32 s40, s40, 0x7800
	s_cmp_lt_u32 s40, 0x4400
	s_cbranch_scc1 .Lbw4_have
	s_mov_b32 s41, 2
	s_sub_i32 s40, s40, 0x4400
	s_cmp_lt_u32 s40, 0x2a80
	s_cbranch_scc1 .Lbw4_have
	s_mov_b32 s41, 3
	s_sub_i32 s40, s40, 0x2a80

;     DEV bool next(int i, Unit& u) const { if (!GroupedOrder::next(i, u)) return false; u.A = A; return true; }
; template <class Epi, class Sched>
; DEV void gemm_phase(LAS unsigned char* lds, const int K, const Sched& S, const Epi& E, const int wid, const int lane) {
;     ...
;     Unit cur, nxt; int ui = 0;
;     if (!S.next(0, cur)) return;
; DEV void gemm_glu(const Frame& F0, int l, int vcu) {
;     const Frame F = refresh(F0);
;     const int li = l >> 1;
;     pg8::PlainOrder S; S.init((const void*)(F.ws + WS_YS), (const bf16_t*)(F.ws + WS_WGLU) + (size_t)li * 512 * 512, 512, (l == DEPTH - 1) ? LATPAD : MPAD, 512, F.G, vcu);
;     EpiGlu E; E.MG = (bf16_t*)(F.ws + WS_MERGED); E.YS = (const bf16_t*)(F.ws + WS_YS); E.bias = GIN(I_ODBGLU) + li * 512;
;     pg8::gemm_phase(F.lds, 512, S, E, F.wave, F.lane);
.Lbw6_skip:
	s_waitcnt lgkmcnt(0)
	v_readlane_b32 s38, v255, 61
	s_cmp_lg_u32 s38, 0
	s_mov_b64 s[2:3], -1
	s_and_b64 vcc, exec, s[56:57]
	s_waitcnt lgkmcnt(0)
	s_barrier
	s_cbranch_vccz .LBB0_1315
	v_readlane_b32 s4, v251, 0
	v_readlane_b32 s5, v251, 1
	v_readlane_b32 s4, v253, 51
	v_readlane_b32 s5, v253, 52
	s_and_b64 s[4:5], s[4:5], exec
	s_cselect_b32 s33, 64, 0x44
	v_readlane_b32 s6, v251, 2
	v_readlane_b32 s7, v251, 3
	s_lshl_b32 s0, s33, 1
	v_readlane_b32 s12, v251, 29
	v_mov_b32_e32 v16, v200
	s_mov_b64 s[2:3], s[6:7]
	s_cmp_ge_i32 s95, s0
	s_cbranch_scc0 .Lglu_gemm
	v_readlane_b32 s2, v255, 51
	s_cmp_lg_u32 s2, 0x100
	s_cbranch_scc1 .LBB0_1270
	v_readlane_b32 s2, v255, 48
	s_cmp_lt_u32 s2, 0x88
	s_cbranch_scc1 .LBB0_1270
	v_readlane_b32 s36, v253, 62
	v_readlane_b32 s3, v251, 29
	s_sub_i32 s2, s2, 0x88
	s_lshl_b32 s2, s2, 3
	s_add_i32 s2, s2, s3
	v_readlane_b32 s6, v255, 53
	v_readlane_b32 s7, v255, 54
	v_readlane_b32 s4, v255, 55
	v_readlane_b32 s5, v255, 56
	v_readlane_b32 s34, v255, 57
	v_readlane_b32 s35, v255, 58
	s_add_u32 s6, s6, 0x2bc8000
	s_addc_u32 s7, s7, 0
	s_mov_b32 s8, 0x10000000
	s_mov_b32 s37, 0x3280
	s_cmp_eq_u32 s36, 1
	s_cbranch_scc1 .Lsl_go
	s_mov_b32 s8, 0x18000000
	s_mov_b32 s37, 0x4580
.Lsl_go:
	s_add_u32 s4, s4, s8
	s_addc_u32 s5, s5, 0
	s_add_u32 s34, s34, s8
	s_addc_u32 s35, s35, 0
	s_add_u32 s6, s6, s8
	s_addc_u32 s7, s7, 0
	s_add_i32 s2, s2, s37
	s_add_i32 s101, s37, 0x780
	s_lshl_b32 s30, s3, 14
	v_and_b32_e32 v120, 31, v200
	v_lshlrev_b32_e32 v2, 2, v120
	v_lshrrev_b32_e32 v3, 5, v200
	v_and_b32_e32 v4, 7, v200
	v_lshrrev_b32_e32 v6, 3, v200
	v_mul_u32_u24_e32 v7, 33, v3
	v_add_u32_e32 v7, v7, v120
	v_lshl_add_u32 v7, v7, 2, s30
	v_add_u32_e32 v8, 0x400, v7
	v_add_u32_e32 v9, 0x840, v7
	v_add_u32_e32 v10, 0xc40, v7
	v_add_u32_e32 v11, 0x1080, v7
	v_add_u32_e32 v12, 0x1480, v7
	v_add_u32_e32 v13, 0x18c0, v7
	v_add_u32_e32 v14, 0x1cc0, v7
	v_mul_u32_u24_e32 v120, 0x108, v4
	v_add_u32_e32 v120, v120, v6
	v_lshl_add_u32 v15, v120, 2, s30
	v_lshl_add_u32 v122, v3, 13, v2
	v_mov_b32_e32 v123, 0
	v_lshlrev_b32_e32 v124, 4, v4
	v_lshl_add_u32 v124, v6, 11, v124
	v_mov_b32_e32 v125, 0
	s_mov_b64 s[40:41], 0x20000
	s_mov_b64 s[42:43], 0x4000
	s_mov_b64 s[44:45], 0x4000

; #define WAVE_LDS_SYNC() do { int _z = 0; (void)emu::wave_xchg(&_z, 4); } while (0)
; #define LAS __attribute__((address_space(3)))
; #define WAVE_LDS_SYNC() asm volatile("s_waitcnt lgkmcnt(0)" ::: "memory")
; #define NT_LOAD(p) __builtin_nontemporal_load(p)
; #define NT_STORE(v, p) __builtin_nontemporal_store((v), (p))
; DEV unsigned pk2(float lo, float hi) { return f2bf(lo) | (f2bf(hi) << 16); }
; DEV unsigned pk2(float lo, float hi) { const f32x2n_t v = {lo, hi}; return __builtin_bit_cast(unsigned, __builtin_convertvector(v, bf16x2n_t)); }
; DEV void tr_item(const float* W, int ldw, int col0, int k0, bf16_t* WT, int K, int row0, LAS float* scr, int lane) {
;     ...
;     for (int i = 0; i < 32; ++i) { const int kk = 2 * i + (lane >> 5); scr[kk * 33 + (lane & 31)] = NT_LOAD(&W[(size_t)(k0 + kk) * ldw + col0 + (lane & 31)]); }
;     WAVE_LDS_SYNC();
;     const int c = lane & 7;
; #pragma unroll
;     for (int j = 0; j < 4; ++j) { const int n = (lane >> 3) + 8 * j; const LAS float* s = scr + (8 * c) * 33 + n;
;         u32x4 o; o.x = pk2(s[0 * 33], s[1 * 33]); o.y = pk2(s[2 * 33], s[3 * 33]); o.z = pk2(s[4 * 33], s[5 * 33]); o.w = pk2(s[6 * 33], s[7 * 33]);
;         NT_STORE(o, (u32x4*)(WT + (size_t)(row0 + n) * K + k0 + 8 * c)); }
;     WAVE_LDS_SYNC();
; DEV void phase_prologue_a(const Frame& F0) {
;     ...
;         constexpr int D_ITEMS = (FF / 64) * 32;
;         for (int it = F.gw; it < NE * D_ITEMS; it += F.NGW) { const int e = it / D_ITEMS, r = it % D_ITEMS, kb = r / 32, nb = r % 32;
;             tr_item(GIN(I_WDOWN) + ((size_t)l * NE + e) * FF * 1024, 1024, 32 * nb, 64 * kb, (bf16_t*)(F.ws + WS_WD) + ((size_t)l * NE + e) * 1024 * FF, FF, 32 * nb, scr, F.lane); }
.Ltk_dn_loop:
	s_lshr_b32 s8, s2, 10
	s_and_b32 s9, s2, 0x3ff
	s_lshr_b32 s10, s9, 5
	s_and_b32 s9, s9, 31
	s_lshl_b32 s24, s10, 18
	s_lshl_b32 s25, s9, 7
	s_add_i32 s24, s24, s25
	s_lshr_b32 s29, s8, 9
	s_lshl_b32 s28, s8, 23
	s_add_u32 s28, s28, s24
	s_addc_u32 s29, s29, 0
	s_add_u32 s28, s28, s4
	s_addc_u32 s29, s29, s5
	s_lshl_b32 s24, s9, 17
	s_lshl_b32 s25, s10, 7
	s_add_i32 s24, s24, s25
	s_lshr_b32 s11, s8, 10
	s_lshl_b32 s10, s8, 22
	s_add_u32 s10, s10, s24
	s_addc_u32 s11, s11, 0
	s_add_u32 s10, s10, s6
	s_addc_u32 s11, s11, s7
	v_lshl_add_u64 v[16:17], s[28:29], 0, v[122:123]
	v_lshl_add_u64 v[18:19], v[16:17], 0, s[44:45]
	v_lshl_add_u64 v[20:21], v[18:19], 0, s[44:45]
	v_lshl_add_u64 v[22:23], v[20:21], 0, s[44:45]
	v_lshl_add_u64 v[24:25], v[22:23], 0, s[44:45]
	v_lshl_add_u64 v[26:27], v[24:25], 0, s[44:45]
	v_lshl_add_u64 v[28:29], v[26:27], 0, s[44:45]
	v_lshl_add_u64 v[30:31], v[28:29], 0, s[44:45]
	global_load_dword v32, v[16:17], off nt
	global_load_dword v33, v[18:19], off nt
	global_load_dword v34, v[20:21], off nt
	global_load_dword v35, v[22:23], off nt
	global_load_dword v36, v[24:25], off nt
	global_load_dword v37, v[26:27], off nt
	global_load_dword v38, v[28:29], off nt
	global_load_dword v39, v[30:31], off nt
	v_lshl_add_u64 v[16:17], v[16:17], 0, s[40:41]
	v_lshl_add_u64 v[18:19], v[18:19], 0, s[40:41]
	v_lshl_add_u64 v[20:21], v[20:21], 0, s[40:41]
	v_lshl_add_u64 v[22:23], v[22:23], 0, s[40:41]
	v_lshl_add_u64 v[24:25], v[24:25], 0, s[40:41]
	v_lshl_add_u64 v[26:27], v[26:27], 0, s[40:41]
	v_lshl_add_u64 v[28:29], v[28:29], 0, s[40:41]
	v_lshl_add_u64 v[30:31], v[30:31], 0, s[40:41]
	global_load_dword v40, v[16:17], off nt
	global_load_dword v41, v[18:19], off nt
	global_load_dword v42, v[20:21], off nt
	global_load_dword v43, v[22:23], off nt
	global_load_dword v44, v[24:25], off nt
	global_load_dword v45, v[26:27], off nt
	global_load_dword v46, v[28:29], off nt
	global_load_dword v47, v[30:31], off nt
	v_lshl_add_u64 v[16:17], v[16:17], 0, s[40:41]
	v_lshl_add_u64 v[18:19], v[18:19], 0, s[40:41]
	v_lshl_add_u64 v[20:21], v[20:21], 0, s[40:41]
	v_lshl_add_u64 v[22:23], v[22:23], 0, s[40:41]
	v_lshl_add_u64 v[24:25], v[24:25], 0, s[40:41]
	v_lshl_add_u64 v[26:27], v[26:27], 0, s[40:41]
	v_lshl_add_u64 v[28:29], v[28:29], 0, s[40:41]
	v_lshl_add_u64 v[30:31], v[30:31], 0, s[40:41]
	global_load_dword v48, v[16:17], off nt
	global_load_dword v49, v[18:19], off nt
	global_load_dword v50, v[20:21], off nt
	global_load_dword v51, v[22:23], off nt
	global_load_dword v52, v[24:25], off nt
	global_load_dword v53, v[26:27], off nt
	global_load_dword v54, v[28:29], off nt
	global_load_dword v55, v[30:31], off nt
	v_lshl_add_u64 v[16:17], v[16:17], 0, s[40:41]
	v_lshl_add_u64 v[18:19], v[18:19], 0, s[40:41]
	v_lshl_add_u64 v[20:21], v[20:21], 0, s[40:41]
	v_lshl_add_u64 v[22:23], v[22:23], 0, s[40:41]
	v_lshl_add_u64 v[24:25], v[24:25], 0, s[40:41]
	v_lshl_add_u64 v[26:27], v[26:27], 0, s[40:41]
	v_lshl_add_u64 v[28:29], v[28:29], 0, s[40:41]
	v_lshl_add_u64 v[30:31], v[30:31], 0, s[40:41]
	global_load_dword v56, v[16:17], off nt
	global_load_dword v57, v[18:19], off nt
	global_load_dword v58, v[20:21], off nt
	global_load_dword v59, v[22:23], off nt
	global_load_dword v60, v[24:25], off nt
	global_load_dword v61, v[26:27], off nt
	global_load_dword v62, v[28:29], off nt
	global_load_dword v63, v[30:31], off nt
	v_lshl_add_u64 v[64:65], s[10:11], 0, v[124:125]
	v_lshl_add_u64 v[66:67], v[64:65], 0, s[42:43]
	v_lshl_add_u64 v[68:69], v[66:67], 0, s[42:43]
	v_lshl_add_u64 v[70:71], v[68:69], 0, s[42:43]
	s_add_i32 s31, s2, 0x400
	s_lshr_b32 s8, s31, 10
	s_and_b32 s9, s31, 0x3ff
	s_lshr_b32 s10, s9, 5
	s_and_b32 s9, s9, 31
	s_lshl_b32 s24, s10, 18
	s_lshl_b32 s25, s9, 7
	s_add_i32 s24, s24, s25
	s_lshr_b32 s29, s8, 9
	s_lshl_b32 s28, s8, 23
	s_add_u32 s28, s28, s24
	s_addc_u32 s29, s29, 0
	s_add_u32 s28, s28, s4
	s_addc_u32 s29, s29, s5
	s_lshl_b32 s24, s9, 17
	s_lshl_b32 s25, s10, 7
	s_add_i32 s24, s24, s25
	s_lshr_b32 s11, s8, 10
	s_lshl_b32 s10, s8, 22
	s_add_u32 s10, s10, s24
	s_addc_u32 s11, s11, 0
	s_add_u32 s10, s10, s6
	s_addc_u32 s11, s11, s7
	v_lshl_add_u64 v[16:17], s[28:29], 0, v[122:123]
	v_lshl_add_u64 v[18:19], v[16:17], 0, s[44:45]
	v_lshl_add_u64 v[20:21], v[18:19], 0, s[44:45]
	v_lshl_add_u64 v[22:23], v[20:21], 0, s[44:45]
	v_lshl_add_u64 v[24:25], v[22:23], 0, s[44:45]
	v_lshl_add_u64 v[26:27], v[24:25], 0, s[44:45]
	v_lshl_add_u64 v[28:29], v[26:27], 0, s[44:45]
	v_lshl_add_u64 v[30:31], v[28:29], 0, s[44:45]
	global_load_dword v162, v[16:17], off nt
	global_load_dword v163, v[18:19], off nt
	global_load_dword v164, v[20:21], off nt
	global_load_dword v165, v[22:23], off nt
	global_load_dword v166, v[24:25], off nt
	global_load_dword v167, v[26:27], off nt
	global_load_dword v168, v[28:29], off nt
	global_load_dword v169, v[30:31], off nt
	v_lshl_add_u64 v[16:17], v[16:17], 0, s[40:41]
	v_lshl_add_u64 v[18:19], v[18:19], 0, s[40:41]
	v_lshl_add_u64 v[20:21], v[20:21], 0, s[40:41]
	v_lshl_add_u64 v[22:23], v[22:23], 0, s[40:41]
	v_lshl_add_u64 v[24:25], v[24:25], 0, s[40:41]
	v_lshl_add_u64 v[26:27], v[26:27], 0, s[40:41]
	v_lshl_add_u64 v[28:29], v[28:29], 0, s[40:41]
	v_lshl_add_u64 v[30:31], v[30:31], 0, s[40:41]
	global_load_dword v170, v[16:17], off nt
	global_load_dword v171, v[18:19], off nt
	global_load_dword v172, v[20:21], off nt
	global_load_dword v173, v[22:23], off nt
	global_load_dword v174, v[24:25], off nt
	global_load_dword v175, v[26:27], off nt
	global_load_dword v176, v[28:29], off nt
	global_load_dword v177, v[30:31], off nt
	v_lshl_add_u64 v[16:17], v[16:17], 0, s[40:41]
; #define WAVE_LDS_SYNC() do { int _z = 0; (void)emu::wave_xchg(&_z, 4); } while (0)
; #define LAS __attribute__((address_space(3)))
; #define WAVE_LDS_SYNC() asm volatile("s_waitcnt lgkmcnt(0)" ::: "memory")
; #define NT_LOAD(p) __builtin_nontemporal_load(p)
; #define NT_STORE(v, p) __builtin_nontemporal_store((v), (p))
; DEV unsigned pk2(float lo, float hi) { return f2bf(lo) | (f2bf(hi) << 16); }
; DEV unsigned pk2(float lo, float hi) { const f32x2n_t v = {lo, hi}; return __builtin_bit_cast(unsigned, __builtin_convertvector(v, bf16x2n_t)); }
; DEV void tr_item(const float* W, int ldw, int col0, int k0, bf16_t* WT, int K, int row0, LAS float* scr, int lane) {
;     ...
;     for (int i = 0; i < 32; ++i) { const int kk = 2 * i + (lane >> 5); scr[kk * 33 + (lane & 31)] = NT_LOAD(&W[(size_t)(k0 + kk) * ldw + col0 + (lane & 31)]); }
;     WAVE_LDS_SYNC();
;     const int c = lane & 7;
; #pragma unroll
;     for (int j = 0; j < 4; ++j) { const int n = (lane >> 3) + 8 * j; const LAS float* s = scr + (8 * c) * 33 + n;
;         u32x4 o; o.x = pk2(s[0 * 33], s[1 * 33]); o.y = pk2(s[2 * 33], s[3 * 33]); o.z = pk2(s[4 * 33], s[5 * 33]); o.w = pk2(s[6 * 33], s[7 * 33]);
;         NT_STORE(o, (u32x4*)(WT + (size_t)(row0 + n) * K + k0 + 8 * c)); }
;     WAVE_LDS_SYNC();
; DEV void phase_prologue_a(const Frame& F0) {
;     ...
;         constexpr int D_ITEMS = (FF / 64) * 32;
;         for (int it = F.gw; it < NE * D_ITEMS; it += F.NGW) { const int e = it / D_ITEMS, r = it % D_ITEMS, kb = r / 32, nb = r % 32;
;             tr_item(GIN(I_WDOWN) + ((size_t)l * NE + e) * FF * 1024, 1024, 32 * nb, 64 * kb, (bf16_t*)(F.ws + WS_WD) + ((size_t)l * NE + e) * 1024 * FF, FF, 32 * nb, scr, F.lane); }
	v_lshl_add_u64 v[18:19], v[18:19], 0, s[40:41]
	v_lshl_add_u64 v[20:21], v[20:21], 0, s[40:41]
	v_lshl_add_u64 v[22:23], v[22:23], 0, s[40:41]
	v_lshl_add_u64 v[24:25], v[24:25], 0, s[40:41]
	v_lshl_add_u64 v[26:27], v[26:27], 0, s[40:41]
	v_lshl_add_u64 v[28:29], v[28:29], 0, s[40:41]
	v_lshl_add_u64 v[30:31], v[30:31], 0, s[40:41]
	global_load_dword v178, v[16:17], off nt
	global_load_dword v179, v[18:19], off nt
	global_load_dword v180, v[20:21], off nt
	global_load_dword v181, v[22:23], off nt
	global_load_dword v182, v[24:25], off nt
	global_load_dword v183, v[26:27], off nt
	global_load_dword v184, v[28:29], off nt
	global_load_dword v185, v[30:31], off nt
	v_lshl_add_u64 v[16:17], v[16:17], 0, s[40:41]
	v_lshl_add_u64 v[18:19], v[18:19], 0, s[40:41]
	v_lshl_add_u64 v[20:21], v[20:21], 0, s[40:41]
	v_lshl_add_u64 v[22:23], v[22:23], 0, s[40:41]
	v_lshl_add_u64 v[24:25], v[24:25], 0, s[40:41]
	v_lshl_add_u64 v[26:27], v[26:27], 0, s[40:41]
	v_lshl_add_u64 v[28:29], v[28:29], 0, s[40:41]
	v_lshl_add_u64 v[30:31], v[30:31], 0, s[40:41]
	global_load_dword v186, v[16:17], off nt
	global_load_dword v187, v[18:19], off nt
	global_load_dword v188, v[20:21], off nt
	global_load_dword v189, v[22:23], off nt
	global_load_dword v190, v[24:25], off nt
	global_load_dword v191, v[26:27], off nt
	global_load_dword v192, v[28:29], off nt
	global_load_dword v193, v[30:31], off nt
	v_lshl_add_u64 v[126:127], s[10:11], 0, v[124:125]
	v_lshl_add_u64 v[128:129], v[126:127], 0, s[42:43]
	v_lshl_add_u64 v[130:131], v[128:129], 0, s[42:43]
	v_lshl_add_u64 v[132:133], v[130:131], 0, s[42:43]
	s_waitcnt vmcnt(62)
	ds_write2_b32 v7, v32, v33 offset1:66
	s_waitcnt vmcnt(60)
	ds_write2_b32 v7, v34, v35 offset0:132 offset1:198
	s_waitcnt vmcnt(58)
	ds_write2_b32 v8, v36, v37 offset0:8 offset1:74
	s_waitcnt vmcnt(56)
	ds_write2_b32 v8, v38, v39 offset0:140 offset1:206
	s_waitcnt vmcnt(54)
	ds_write2_b32 v9, v40, v41 offset1:66
	s_waitcnt vmcnt(52)
	ds_write2_b32 v9, v42, v43 offset0:132 offset1:198
	s_waitcnt vmcnt(50)
	ds_write2_b32 v10, v44, v45 offset0:8 offset1:74
	s_waitcnt vmcnt(48)
	ds_write2_b32 v10, v46, v47 offset0:140 offset1:206
	s_waitcnt vmcnt(46)
	ds_write2_b32 v11, v48, v49 offset1:66
	s_waitcnt vmcnt(44)
	ds_write2_b32 v11, v50, v51 offset0:132 offset1:198
	s_waitcnt vmcnt(42)
	ds_write2_b32 v12, v52, v53 offset0:8 offset1:74
	s_waitcnt vmcnt(40)
	ds_write2_b32 v12, v54, v55 offset0:140 offset1:206
	s_waitcnt vmcnt(38)
	ds_write2_b32 v13, v56, v57 offset1:66
	s_waitcnt vmcnt(36)
	ds_write2_b32 v13, v58, v59 offset0:132 offset1:198
	s_waitcnt vmcnt(34)
	ds_write2_b32 v14, v60, v61 offset0:8 offset1:74
	s_waitcnt vmcnt(32)
	ds_write2_b32 v14, v62, v63 offset0:140 offset1:206
	ds_read2_b32 v[72:73], v15 offset1:8
	ds_read2_b32 v[74:75], v15 offset0:33 offset1:41
	ds_read2_b32 v[76:77], v15 offset0:66 offset1:74
	ds_read2_b32 v[78:79], v15 offset0:99 offset1:107
	ds_read2_b32 v[80:81], v15 offset0:132 offset1:140
	ds_read2_b32 v[82:83], v15 offset0:165 offset1:173
	ds_read2_b32 v[84:85], v15 offset0:198 offset1:206
	ds_read2_b32 v[86:87], v15 offset0:231 offset1:239
	ds_read2_b32 v[88:89], v15 offset0:16 offset1:24
	ds_read2_b32 v[90:91], v15 offset0:49 offset1:57
	ds_read2_b32 v[92:93], v15 offset0:82 offset1:90
	ds_read2_b32 v[94:95], v15 offset0:115 offset1:123
	s_waitcnt lgkmcnt(4)
	v_cvt_pk_bf16_f32 v104, v72, v74
	v_cvt_pk_bf16_f32 v105, v76, v78
	v_cvt_pk_bf16_f32 v106, v80, v82
	v_cvt_pk_bf16_f32 v107, v84, v86
	v_cvt_pk_bf16_f32 v108, v73, v75
	v_cvt_pk_bf16_f32 v109, v77, v79
	v_cvt_pk_bf16_f32 v110, v81, v83
	v_cvt_pk_bf16_f32 v111, v85, v87
	ds_read2_b32 v[96:97], v15 offset0:148 offset1:156
	ds_read2_b32 v[98:99], v15 offset0:181 offset1:189
	ds_read2_b32 v[100:101], v15 offset0:214 offset1:222
	ds_read2_b32 v[102:103], v15 offset0:247 offset1:255
	global_store_dwordx4 v[64:65], v[104:107], off nt
	global_store_dwordx4 v[66:67], v[108:111], off nt
	s_waitcnt lgkmcnt(0)
	v_cvt_pk_bf16_f32 v112, v88, v90
	v_cvt_pk_bf16_f32 v113, v92, v94
	v_cvt_pk_bf16_f32 v114, v96, v98
	v_cvt_pk_bf16_f32 v115, v100, v102
	v_cvt_pk_bf16_f32 v116, v89, v91
	v_cvt_pk_bf16_f32 v117, v93, v95
	v_cvt_pk_bf16_f32 v118, v97, v99
	v_cvt_pk_bf16_f32 v119, v101, v103
	global_store_dwordx4 v[68:69], v[112:115], off nt
	global_store_dwordx4 v[70:71], v[116:119], off nt
	s_waitcnt vmcnt(34)
; #define WAVE_LDS_SYNC() do { int _z = 0; (void)emu::wave_xchg(&_z, 4); } while (0)
; #define LAS __attribute__((address_space(3)))
; #define WAVE_LDS_SYNC() asm volatile("s_waitcnt lgkmcnt(0)" ::: "memory")
; #define NT_LOAD(p) __builtin_nontemporal_load(p)
; #define NT_STORE(v, p) __builtin_nontemporal_store((v), (p))
; DEV unsigned pk2(float lo, float hi) { return f2bf(lo) | (f2bf(hi) << 16); }
; DEV unsigned pk2(float lo, float hi) { const f32x2n_t v = {lo, hi}; return __builtin_bit_cast(unsigned, __builtin_convertvector(v, bf16x2n_t)); }
; DEV void tr_item(const float* W, int ldw, int col0, int k0, bf16_t* WT, int K, int row0, LAS float* scr, int lane) {
;     ...
;     for (int i = 0; i < 32; ++i) { const int kk = 2 * i + (lane >> 5); scr[kk * 33 + (lane & 31)] = NT_LOAD(&W[(size_t)(k0 + kk) * ldw + col0 + (lane & 31)]); }
;     WAVE_LDS_SYNC();
;     const int c = lane & 7;
; #pragma unroll
;     for (int j = 0; j < 4; ++j) { const int n = (lane >> 3) + 8 * j; const LAS float* s = scr + (8 * c) * 33 + n;
;         u32x4 o; o.x = pk2(s[0 * 33], s[1 * 33]); o.y = pk2(s[2 * 33], s[3 * 33]); o.z = pk2(s[4 * 33], s[5 * 33]); o.w = pk2(s[6 * 33], s[7 * 33]);
;         NT_STORE(o, (u32x4*)(WT + (size_t)(row0 + n) * K + k0 + 8 * c)); }
;     WAVE_LDS_SYNC();
; DEV void phase_prologue_a(const Frame& F0) {
;     ...
;         constexpr int GU_NB = 2 * FF / 32, GU_ITEMS = 16 * GU_NB;
;         for (int it = F.gw; it < NE * GU_ITEMS; it += F.NGW) { const int e = it / GU_ITEMS, r = it % GU_ITEMS, kb = r / GU_NB, nb = r % GU_NB; const int d0 = 32 * nb, j = d0 >> 8, w = d0 & 255;
;             const float* src = (w < 128 ? GIN(I_WGATE) : GIN(I_WUP)) + ((size_t)l * NE + e) * 1024 * FF;
;             tr_item(src, FF, 128 * j + (w & 127), 64 * kb, (bf16_t*)(F.ws + WS_WGU) + ((size_t)l * NE + e) * 2 * FF * 1024, 1024, d0, scr, F.lane); }
;         constexpr int D_ITEMS = (FF / 64) * 32;
;         for (int it = F.gw; it < NE * D_ITEMS; it += F.NGW) { const int e = it / D_ITEMS, r = it % D_ITEMS, kb = r / 32, nb = r % 32;
;             tr_item(GIN(I_WDOWN) + ((size_t)l * NE + e) * FF * 1024, 1024, 32 * nb, 64 * kb, (bf16_t*)(F.ws + WS_WD) + ((size_t)l * NE + e) * 1024 * FF, FF, 32 * nb, scr, F.lane); }
	ds_write2_b32 v7, v162, v163 offset1:66
	s_waitcnt vmcnt(32)
	ds_write2_b32 v7, v164, v165 offset0:132 offset1:198
	s_waitcnt vmcnt(30)
	ds_write2_b32 v8, v166, v167 offset0:8 offset1:74
	s_waitcnt vmcnt(28)
	ds_write2_b32 v8, v168, v169 offset0:140 offset1:206
	s_waitcnt vmcnt(26)
	ds_write2_b32 v9, v170, v171 offset1:66
	s_waitcnt vmcnt(24)
	ds_write2_b32 v9, v172, v173 offset0:132 offset1:198
	s_waitcnt vmcnt(22)
	ds_write2_b32 v10, v174, v175 offset0:8 offset1:74
	s_waitcnt vmcnt(20)
	ds_write2_b32 v10, v176, v177 offset0:140 offset1:206
	s_waitcnt vmcnt(18)
	ds_write2_b32 v11, v178, v179 offset1:66
	s_waitcnt vmcnt(16)
	ds_write2_b32 v11, v180, v181 offset0:132 offset1:198
	s_waitcnt vmcnt(14)
	ds_write2_b32 v12, v182, v183 offset0:8 offset1:74
	s_waitcnt vmcnt(12)
	ds_write2_b32 v12, v184, v185 offset0:140 offset1:206
	s_waitcnt vmcnt(10)
	ds_write2_b32 v13, v186, v187 offset1:66
	s_waitcnt vmcnt(8)
	ds_write2_b32 v13, v188, v189 offset0:132 offset1:198
	s_waitcnt vmcnt(6)
	ds_write2_b32 v14, v190, v191 offset0:8 offset1:74
	s_waitcnt vmcnt(4)
	ds_write2_b32 v14, v192, v193 offset0:140 offset1:206
	ds_read2_b32 v[72:73], v15 offset1:8
	ds_read2_b32 v[74:75], v15 offset0:33 offset1:41
	ds_read2_b32 v[76:77], v15 offset0:66 offset1:74
	ds_read2_b32 v[78:79], v15 offset0:99 offset1:107
	ds_read2_b32 v[80:81], v15 offset0:132 offset1:140
	ds_read2_b32 v[82:83], v15 offset0:165 offset1:173
	ds_read2_b32 v[84:85], v15 offset0:198 offset1:206
	ds_read2_b32 v[86:87], v15 offset0:231 offset1:239
	ds_read2_b32 v[88:89], v15 offset0:16 offset1:24
	ds_read2_b32 v[90:91], v15 offset0:49 offset1:57
	ds_read2_b32 v[92:93], v15 offset0:82 offset1:90
	ds_read2_b32 v[94:95], v15 offset0:115 offset1:123
	s_waitcnt lgkmcnt(4)
	v_cvt_pk_bf16_f32 v104, v72, v74
	v_cvt_pk_bf16_f32 v105, v76, v78
	v_cvt_pk_bf16_f32 v106, v80, v82
	v_cvt_pk_bf16_f32 v107, v84, v86
	v_cvt_pk_bf16_f32 v108, v73, v75
	v_cvt_pk_bf16_f32 v109, v77, v79
	v_cvt_pk_bf16_f32 v110, v81, v83
	v_cvt_pk_bf16_f32 v111, v85, v87
	ds_read2_b32 v[96:97], v15 offset0:148 offset1:156
	ds_read2_b32 v[98:99], v15 offset0:181 offset1:189
	ds_read2_b32 v[100:101], v15 offset0:214 offset1:222
	ds_read2_b32 v[102:103], v15 offset0:247 offset1:255
	global_store_dwordx4 v[126:127], v[104:107], off nt
	global_store_dwordx4 v[128:129], v[108:111], off nt
	s_waitcnt lgkmcnt(0)
	v_cvt_pk_bf16_f32 v112, v88, v90
	v_cvt_pk_bf16_f32 v113, v92, v94
	v_cvt_pk_bf16_f32 v114, v96, v98
	v_cvt_pk_bf16_f32 v115, v100, v102
	v_cvt_pk_bf16_f32 v116, v89, v91
	v_cvt_pk_bf16_f32 v117, v93, v95
	v_cvt_pk_bf16_f32 v118, v97, v99
	v_cvt_pk_bf16_f32 v119, v101, v103
	global_store_dwordx4 v[130:131], v[112:115], off nt
	global_store_dwordx4 v[132:133], v[116:119], off nt
	s_add_i32 s2, s2, 0x800
	s_cmp_lt_u32 s2, 0x2f00
	s_cbranch_scc1 .Ltk_dn_loop
	s_branch .LBB0_1705
.Ltk_gu:
	v_readlane_b32 s4, v255, 55
	v_readlane_b32 s5, v255, 56
	v_readlane_b32 s34, v255, 57
	v_readlane_b32 s35, v255, 58
	s_add_u32 s6, s6, 0x2bc8000
	s_addc_u32 s7, s7, 0
	s_mov_b32 s8, 0x10000000
	s_mov_b32 s37, 0x2a80
	s_cmp_eq_u32 s36, 1
	s_cbranch_scc1 .Ltk_go
	s_mov_b32 s8, 0x18000000
	s_mov_b32 s37, 0x3580
	s_cmp_eq_u32 s36, 2
	s_cbranch_scc1 .Ltk_go
	s_mov_b32 s37, 0x3d80
.Ltk_go:
	s_add_u32 s4, s4, s8
	s_addc_u32 s5, s5, 0
	s_add_u32 s34, s34, s8
	s_addc_u32 s35, s35, 0
	s_add_u32 s6, s6, s8
	s_addc_u32 s7, s7, 0
	s_add_i32 s2, s2, s37
	s_add_i32 s101, s37, 0x800
	s_lshl_b32 s30, s3, 14
	v_and_b32_e32 v120, 31, v200
	v_lshlrev_b32_e32 v2, 2, v120
	v_lshrrev_b32_e32 v3, 5, v200
	v_and_b32_e32 v4, 7, v200
	v_lshrrev_b32_e32 v6, 3, v200
	v_mul_u32_u24_e32 v7, 33, v3
	v_add_u32_e32 v7, v7, v120
	v_lshl_add_u32 v7, v7, 2, s30
	v_add_u32_e32 v8, 0x400, v7
	v_add_u32_e32 v9, 0x840, v7
	v_add_u32_e32 v10, 0xc40, v7
	v_add_u32_e32 v11, 0x1080, v7
	v_add_u32_e32 v12, 0x1480, v7
	v_add_u32_e32 v13, 0x18c0, v7
	v_add_u32_e32 v14, 0x1cc0, v7
	v_mul_u32_u24_e32 v120, 0x108, v4
	v_add_u32_e32 v120, v120, v6
	v_lshl_add_u32 v15, v120, 2, s30
	v_lshl_add_u32 v122, v3, 13, v2
	v_mov_b32_e32 v123, 0
	v_lshlrev_b32_e32 v124, 4, v4
	v_lshl_add_u32 v124, v6, 11, v124
	v_mov_b32_e32 v125, 0
	s_mov_b64 s[40:41], 0x20000
	s_mov_b64 s[42:43], 0x4000
	s_mov_b64 s[44:45], 0x4000
